# attnC step body: group barrier arrival issued before the last four PV MFMAs (same as attnA)
# baseline (speedup 1.0000x reference)
.LBB0_1057:
	v_cmp_le_i32_e32 vcc, s12, v187
	s_and_saveexec_b64 s[10:11], vcc
	s_cbranch_execz .LBB0_1059
	s_lshl_b32 s12, s12, 15
	s_and_b32 s12, s12, 0x8000
	s_add_i32 s12, s80, s12
	v_add3_u32 v220, s12, v186, v190
	v_add_u32_e32 v221, v220, v199
	v_add_u32_e32 v222, v220, v200
	v_add_u32_e32 v223, v220, v201
	v_add_u32_e32 v224, v220, v202
	v_add_u32_e32 v225, v220, v203
	v_add_u32_e32 v226, v220, v216
	v_add_u32_e32 v227, v220, v217
	v_add_u32_e32 v228, v220, v218
	v_lshrrev_b32_e32 v229, v189, v168
	v_lshrrev_b32_e32 v230, v189, v169
	v_add3_u32 v0, s12, v191, v188
	ds_read_b128 v[2:5], v0
	ds_read_b128 v[8:11], v0 offset:8192
	v_add3_u32 v0, s12, v192, v188
	ds_read_b128 v[12:15], v0
	s_waitcnt lgkmcnt(2)
	v_mfma_f32_32x32x16_bf16 v[112:127], v[2:5], v[156:159], v[16:31]
	ds_read_b128 v[2:5], v0 offset:8192
	s_waitcnt lgkmcnt(2)
	v_mfma_f32_32x32x16_bf16 v[96:111], v[8:11], v[156:159], v[16:31]
	v_add3_u32 v0, s12, v193, v188
	ds_read_b128 v[8:11], v0
	s_waitcnt lgkmcnt(2)
	v_mfma_f32_32x32x16_bf16 v[112:127], v[12:15], v[128:131], v[112:127]
	ds_read_b128 v[12:15], v0 offset:8192
	s_waitcnt lgkmcnt(2)
	v_mfma_f32_32x32x16_bf16 v[96:111], v[2:5], v[128:131], v[96:111]
	v_add3_u32 v0, s12, v194, v188
	ds_read_b128 v[2:5], v0
	s_waitcnt lgkmcnt(2)
	v_mfma_f32_32x32x16_bf16 v[112:127], v[8:11], v[132:135], v[112:127]
	ds_read_b128 v[8:11], v0 offset:8192
	s_waitcnt lgkmcnt(2)
	v_mfma_f32_32x32x16_bf16 v[96:111], v[12:15], v[132:135], v[96:111]
	v_add3_u32 v0, s12, v195, v188
	ds_read_b128 v[12:15], v0
	s_waitcnt lgkmcnt(2)
	v_mfma_f32_32x32x16_bf16 v[112:127], v[2:5], v[136:139], v[112:127]
	ds_read_b128 v[2:5], v0 offset:8192
	s_waitcnt lgkmcnt(2)
	v_mfma_f32_32x32x16_bf16 v[96:111], v[8:11], v[136:139], v[96:111]
	v_add3_u32 v0, s12, v196, v188
	ds_read_b128 v[8:11], v0
	s_waitcnt lgkmcnt(2)
	v_mfma_f32_32x32x16_bf16 v[112:127], v[12:15], v[140:143], v[112:127]
	ds_read_b128 v[12:15], v0 offset:8192
	s_waitcnt lgkmcnt(2)
	v_mfma_f32_32x32x16_bf16 v[96:111], v[2:5], v[140:143], v[96:111]
	v_add3_u32 v0, s12, v197, v188
	ds_read_b128 v[2:5], v0
	s_waitcnt lgkmcnt(2)
	v_mfma_f32_32x32x16_bf16 v[112:127], v[8:11], v[144:147], v[112:127]
	ds_read_b128 v[8:11], v0 offset:8192
	s_waitcnt lgkmcnt(2)
	v_mfma_f32_32x32x16_bf16 v[96:111], v[12:15], v[144:147], v[96:111]
	v_add3_u32 v0, s12, v198, v188
	ds_read_b128 v[12:15], v0
	s_waitcnt lgkmcnt(2)
	v_mfma_f32_32x32x16_bf16 v[112:127], v[2:5], v[148:151], v[112:127]
	ds_read_b128 v[2:5], v0 offset:8192
	s_waitcnt lgkmcnt(2)
	v_mfma_f32_32x32x16_bf16 v[96:111], v[8:11], v[148:151], v[96:111]
	s_waitcnt lgkmcnt(1)
	v_mfma_f32_32x32x16_bf16 v[112:127], v[12:15], v[152:155], v[112:127]
	s_waitcnt lgkmcnt(0)
	v_mfma_f32_32x32x16_bf16 v[96:111], v[2:5], v[152:155], v[96:111]
	ds_read_b64 v[8:9], v221 offset:16384
	ds_read_b64 v[10:11], v222 offset:16384
	ds_read_b64 v[12:13], v221 offset:20480
	ds_read_b64 v[14:15], v222 offset:20480
	ds_read_b64 v[236:237], v221 offset:28672
	ds_read_b64 v[238:239], v222 offset:28672
	s_nop 3
	v_exp_f32_e32 v112, v112
	v_exp_f32_e32 v113, v113
	v_exp_f32_e32 v114, v114
	v_exp_f32_e32 v115, v115
	v_exp_f32_e32 v116, v116
	v_exp_f32_e32 v117, v117
	v_exp_f32_e32 v118, v118
	v_exp_f32_e32 v119, v119
	v_bfe_i32 v231, v229, 0, 1
	v_and_b32_e32 v112, v112, v231
	v_bfe_i32 v232, v229, 1, 1
	v_and_b32_e32 v113, v113, v232
	v_bfe_i32 v231, v229, 2, 1
	v_and_b32_e32 v114, v114, v231
	v_bfe_i32 v232, v229, 3, 1
	v_and_b32_e32 v115, v115, v232
	v_bfe_i32 v231, v229, 8, 1
	v_and_b32_e32 v116, v116, v231
	v_bfe_i32 v232, v229, 9, 1
	v_and_b32_e32 v117, v117, v232
	v_bfe_i32 v231, v229, 10, 1
	v_and_b32_e32 v118, v118, v231
	v_bfe_i32 v232, v229, 11, 1
	v_and_b32_e32 v119, v119, v232
	v_cvt_pk_bf16_f32 v2, v112, v113
	v_cvt_pk_bf16_f32 v3, v114, v115
	v_cvt_pk_bf16_f32 v4, v116, v117
	v_cvt_pk_bf16_f32 v5, v118, v119
	v_add_f32_e32 v0, 0, v112
	v_add_f32_e32 v0, v113, v0
	v_add_f32_e32 v0, v114, v0
	v_add_f32_e32 v0, v115, v0
	v_add_f32_e32 v0, v116, v0
	v_add_f32_e32 v0, v117, v0
	v_add_f32_e32 v0, v118, v0
	v_add_f32_e32 v0, v119, v0
	ds_read_b64 v[240:241], v221 offset:24576
	ds_read_b64 v[242:243], v222 offset:24576
	ds_read_b64 v[244:245], v223 offset:16384
	ds_read_b64 v[246:247], v224 offset:16384
	s_waitcnt lgkmcnt(8)
	v_mfma_f32_32x32x16_bf16 v[80:95], v[8:11], v[2:5], v[80:95]
	ds_read_b64 v[112:113], v223 offset:20480
	ds_read_b64 v[114:115], v224 offset:20480
	v_exp_f32_e32 v120, v120
	v_exp_f32_e32 v121, v121
	s_waitcnt lgkmcnt(8)
	v_mfma_f32_32x32x16_bf16 v[64:79], v[12:15], v[2:5], v[64:79]
	ds_read_b64 v[116:117], v223 offset:24576
	ds_read_b64 v[118:119], v224 offset:24576
	v_exp_f32_e32 v122, v122
	v_exp_f32_e32 v123, v123
	v_bfe_i32 v231, v229, 16, 1
	v_and_b32_e32 v120, v120, v231
	v_bfe_i32 v232, v229, 17, 1
	v_and_b32_e32 v121, v121, v232
	v_add_f32_e32 v0, v120, v0
	v_add_f32_e32 v0, v121, v0
	s_waitcnt lgkmcnt(8)
	v_mfma_f32_32x32x16_bf16 v[32:47], v[236:239], v[2:5], v[32:47]
	ds_read_b64 v[8:9], v223 offset:28672
	ds_read_b64 v[10:11], v224 offset:28672
	v_exp_f32_e32 v124, v124
	v_exp_f32_e32 v125, v125
	v_bfe_i32 v231, v229, 18, 1
	v_and_b32_e32 v122, v122, v231
	v_bfe_i32 v232, v229, 19, 1
	v_and_b32_e32 v123, v123, v232
	v_add_f32_e32 v0, v122, v0
	v_add_f32_e32 v0, v123, v0
	s_waitcnt lgkmcnt(8)
	v_mfma_f32_32x32x16_bf16 v[48:63], v[240:243], v[2:5], v[48:63]
	ds_read_b64 v[12:13], v225 offset:16384
	ds_read_b64 v[14:15], v226 offset:16384
	v_exp_f32_e32 v126, v126
	v_exp_f32_e32 v127, v127
	v_bfe_i32 v231, v229, 24, 1
	v_and_b32_e32 v124, v124, v231
	v_bfe_i32 v232, v229, 25, 1
	v_and_b32_e32 v125, v125, v232
	v_add_f32_e32 v0, v124, v0
	v_add_f32_e32 v0, v125, v0
	v_bfe_i32 v231, v229, 26, 1
	v_and_b32_e32 v126, v126, v231
	v_bfe_i32 v232, v229, 27, 1
	v_and_b32_e32 v127, v127, v232
	v_add_f32_e32 v0, v126, v0
	v_add_f32_e32 v0, v127, v0
	v_cvt_pk_bf16_f32 v2, v120, v121
	v_cvt_pk_bf16_f32 v3, v122, v123
	v_cvt_pk_bf16_f32 v4, v124, v125
	v_cvt_pk_bf16_f32 v5, v126, v127
	s_nop 1
	ds_read_b64 v[236:237], v225 offset:20480
	ds_read_b64 v[238:239], v226 offset:20480
	s_waitcnt lgkmcnt(10)
	v_mfma_f32_32x32x16_bf16 v[80:95], v[244:247], v[2:5], v[80:95]
	ds_read_b64 v[240:241], v225 offset:24576
	ds_read_b64 v[242:243], v226 offset:24576
	v_exp_f32_e32 v96, v96
	v_exp_f32_e32 v97, v97
	s_waitcnt lgkmcnt(10)
	v_mfma_f32_32x32x16_bf16 v[64:79], v[112:115], v[2:5], v[64:79]
	ds_read_b64 v[120:121], v225 offset:28672
	ds_read_b64 v[122:123], v226 offset:28672
	v_exp_f32_e32 v98, v98
	v_exp_f32_e32 v99, v99
	v_bfe_i32 v231, v230, 0, 1
	v_and_b32_e32 v96, v96, v231
	v_bfe_i32 v232, v230, 1, 1
	v_and_b32_e32 v97, v97, v232
	v_add_f32_e32 v0, v96, v0
	v_add_f32_e32 v0, v97, v0
	s_waitcnt lgkmcnt(10)
	v_mfma_f32_32x32x16_bf16 v[48:63], v[116:119], v[2:5], v[48:63]
	ds_read_b64 v[124:125], v227 offset:16384
	ds_read_b64 v[126:127], v228 offset:16384
	v_exp_f32_e32 v100, v100
	v_exp_f32_e32 v101, v101
	v_bfe_i32 v231, v230, 2, 1
	v_and_b32_e32 v98, v98, v231
	v_bfe_i32 v232, v230, 3, 1
	v_and_b32_e32 v99, v99, v232
	v_add_f32_e32 v0, v98, v0
	v_add_f32_e32 v0, v99, v0
	s_waitcnt lgkmcnt(10)
	v_mfma_f32_32x32x16_bf16 v[32:47], v[8:11], v[2:5], v[32:47]
	ds_read_b64 v[244:245], v227 offset:20480
	ds_read_b64 v[246:247], v228 offset:20480
	v_exp_f32_e32 v102, v102
	v_exp_f32_e32 v103, v103
	v_bfe_i32 v231, v230, 8, 1
	v_and_b32_e32 v100, v100, v231
	v_bfe_i32 v232, v230, 9, 1
	v_and_b32_e32 v101, v101, v232
	v_add_f32_e32 v0, v100, v0
	v_add_f32_e32 v0, v101, v0
	v_bfe_i32 v231, v230, 10, 1
	v_and_b32_e32 v102, v102, v231
	v_bfe_i32 v232, v230, 11, 1
	v_and_b32_e32 v103, v103, v232
	v_add_f32_e32 v0, v102, v0
	v_add_f32_e32 v0, v103, v0
	v_cvt_pk_bf16_f32 v2, v96, v97
	v_cvt_pk_bf16_f32 v3, v98, v99
	v_cvt_pk_bf16_f32 v4, v100, v101
	v_cvt_pk_bf16_f32 v5, v102, v103
	s_nop 1
	ds_read_b64 v[112:113], v227 offset:24576
	ds_read_b64 v[114:115], v228 offset:24576
	s_waitcnt lgkmcnt(12)
	v_mfma_f32_32x32x16_bf16 v[80:95], v[12:15], v[2:5], v[80:95]
	ds_read_b64 v[116:117], v227 offset:28672
	ds_read_b64 v[118:119], v228 offset:28672
	v_exp_f32_e32 v104, v104
	v_exp_f32_e32 v105, v105
	s_waitcnt lgkmcnt(12)
	v_mfma_f32_32x32x16_bf16 v[64:79], v[236:239], v[2:5], v[64:79]
	v_exp_f32_e32 v106, v106
	v_exp_f32_e32 v107, v107
	v_bfe_i32 v231, v230, 16, 1
	v_and_b32_e32 v104, v104, v231
	v_bfe_i32 v232, v230, 17, 1
	v_and_b32_e32 v105, v105, v232
	v_add_f32_e32 v0, v104, v0
	v_add_f32_e32 v0, v105, v0
	s_waitcnt lgkmcnt(10)
	v_mfma_f32_32x32x16_bf16 v[48:63], v[240:243], v[2:5], v[48:63]
	v_exp_f32_e32 v108, v108
	v_exp_f32_e32 v109, v109
	v_bfe_i32 v231, v230, 18, 1
	v_and_b32_e32 v106, v106, v231
	v_bfe_i32 v232, v230, 19, 1
	v_and_b32_e32 v107, v107, v232
	v_add_f32_e32 v0, v106, v0
	v_add_f32_e32 v0, v107, v0
	s_waitcnt lgkmcnt(8)
	v_mfma_f32_32x32x16_bf16 v[32:47], v[120:123], v[2:5], v[32:47]
	v_exp_f32_e32 v110, v110
	v_exp_f32_e32 v111, v111
	v_bfe_i32 v231, v230, 24, 1
	v_and_b32_e32 v108, v108, v231
	v_bfe_i32 v232, v230, 25, 1
	v_and_b32_e32 v109, v109, v232
	v_add_f32_e32 v0, v108, v0
	v_add_f32_e32 v0, v109, v0
	v_bfe_i32 v231, v230, 26, 1
	v_and_b32_e32 v110, v110, v231
	v_bfe_i32 v232, v230, 27, 1
	v_and_b32_e32 v111, v111, v232
	v_add_f32_e32 v0, v110, v0
	v_add_f32_e32 v0, v111, v0
	v_cvt_pk_bf16_f32 v2, v104, v105
	v_cvt_pk_bf16_f32 v3, v106, v107
	v_cvt_pk_bf16_f32 v4, v108, v109
	v_cvt_pk_bf16_f32 v5, v110, v111
	s_nop 1
	s_waitcnt vmcnt(0) lgkmcnt(0)
	s_mov_b64 s[24:25], exec
	s_mov_b64 exec, 1
	v_mov_b32_e32 v248, s33
	v_mov_b32_e32 v249, 1
	ds_add_u32 v248, v249 offset:8
	s_mov_b64 exec, s[24:25]
	s_waitcnt lgkmcnt(6)
	v_mfma_f32_32x32x16_bf16 v[80:95], v[124:127], v[2:5], v[80:95]
	s_waitcnt lgkmcnt(4)
	v_mfma_f32_32x32x16_bf16 v[64:79], v[244:247], v[2:5], v[64:79]
	s_waitcnt lgkmcnt(2)
	v_mfma_f32_32x32x16_bf16 v[48:63], v[112:115], v[2:5], v[48:63]
	s_waitcnt lgkmcnt(0)
	v_mfma_f32_32x32x16_bf16 v[32:47], v[116:119], v[2:5], v[32:47]
	v_add_f32_e32 v219, v219, v0
	s_branch .LBB0_1062
